# cross-phase operand prefetch: workgroups that leave P2 early touch their share of the gate GEMM's first XN panels and gate-weight panels before the P2->P3 seam
# speedup vs baseline: 1.0026x; 1.0026x over previous
; #define PH_IDS() int tid = threadIdx.x; asm volatile("" : "+v"(tid)); const int lane = tid & 63
; #define SEAM(k) do { if (IN(k) && IN((k) + 1)) { if ((k) == 0) cg::this_grid().sync(); else xcd_barrier(xbar); } } while (0)
; __device__ __forceinline__ void sgu_item(LAS unsigned char* lds, const bf16* VA, bf16* AO, const bf16* ZA, const bf16* WSM, const float* ln_g, const float* ln_b, const float* b_sp, ...
;     ...
;     {
;         const int row = tid >> 2, q = tid & 3;
;         const v4u* up0 = (const v4u*)(AO + (size_t)(r0 + row) * 2048 + g * 128 + q * 32);
;         const v4u* zp0 = (const v4u*)(ZA + (size_t)(r0 + row) * 1024 + g * 128 + q * 32);
; #pragma unroll
;         for (int i = 0; i < 4; ++i) { ureg[i] = up0[i]; zreg[i] = zp0[i]; }
;     }
; __global__ void __launch_bounds__(NWAVES * 64, 2) fwd_mega(Args args) {
;     ...
;         if (vcu & 1) { fa::fox_phase((char*)lds_raw, FT, vcu, G); __syncthreads(); { PH_IDS(); v4u vin[4];
;                 if (vcu < 2048) { const v4u* vp = (const v4u*)(VA + (size_t)((vcu >> 3) * 128 + (tid >> 2)) * 1024 + (vcu & 7) * 128 + (tid & 3) * 32);
; #pragma unroll
;                     for (int i = 0; i < 4; ++i) vin[i] = vp[i]; }
;                 for (int it = vcu; it < 2048; it += G) { const int itn = it + G; sgu_item(lds, VA, AO, ZA, WSM, args.in[3], args.in[4], args.in[6], it >> 3, it & 7, tid, lane, wave, vin, itn >> 3, itn & 7, itn < 2048); } } }
;         else { { PH_IDS(); v4u vin[4];
;                 if (vcu < 2048) { const v4u* vp = (const v4u*)(VA + (size_t)((vcu >> 3) * 128 + (tid >> 2)) * 1024 + (vcu & 7) * 128 + (tid & 3) * 32);
; #pragma unroll
;                     for (int i = 0; i < 4; ++i) vin[i] = vp[i]; }
;                 for (int it = vcu; it < 2048; it += G) { const int itn = it + G; sgu_item(lds, VA, AO, ZA, WSM, args.in[3], args.in[4], args.in[6], it >> 3, it & 7, tid, lane, wave, vin, itn >> 3, itn & 7, itn < 2048); } } __syncthreads(); fa::fox_phase((char*)lds_raw, FT, vcu, G); }
;     }
;     SEAM(2);
.LBB0_263:
	s_waitcnt vmcnt(0)
	s_barrier
	s_bitcmp1_b32 s86, 3
	s_cbranch_scc1 .LBB0_271
	v_and_b32_e32 v1, 63, v0
	v_lshlrev_b32_e32 v1, 7, v1
	v_lshrrev_b32_e32 v2, 6, v0
	v_lshl_or_b32 v1, v2, 15, v1
	s_lshr_b32 s96, s86, 5
	s_lshl_b32 s98, s96, 23
	s_and_b32 s97, s86, 7
	s_bfe_u32 s99, s86, 0x10004
	s_lshl_b32 s99, s99, 3
	s_or_b32 s97, s97, s99
	s_lshl_b32 s99, s97, 18
	s_add_u32 s98, s98, s99
	s_add_u32 s98, s26, s98
	s_addc_u32 s99, s27, 0
	v_add_u32_e32 v3, 0x2000, v1
	v_add_u32_e32 v4, 0x4000, v1
	v_add_u32_e32 v5, 0x6000, v1
	global_load_dword v6, v1, s[98:99]
	global_load_dword v7, v3, s[98:99]
	global_load_dword v8, v4, s[98:99]
	global_load_dword v9, v5, s[98:99]
	s_cmp_lt_u32 s88, 2
	s_cbranch_scc0 .Lxp_done
	s_lshl_b32 s96, s96, 4
	s_or_b32 s96, s96, s97
	s_lshl_b32 s96, s96, 14
	s_add_u32 s96, s96, 0x1200000
	s_add_u32 s96, s28, s96
	s_addc_u32 s97, s29, 0
	v_and_b32_e32 v3, 63, v0
	v_lshlrev_b32_e32 v3, 7, v3
	v_lshl_or_b32 v3, v2, 13, v3
	global_load_dword v10, v3, s[96:97]
.Lxp_done:
	s_branch .LBB0_324
.LBB0_271:
.Lsgu_entry:
	s_cmpk_gt_i32 s86, 0x7ff
	s_cbranch_scc1 .Lsgu_done
	v_lshrrev_b32_e32 v10, 2, v0
	v_and_b32_e32 v11, 3, v0
	v_lshlrev_b32_e32 v12, 6, v11
	v_and_b32_e32 v13, 15, v0
	v_bfe_u32 v14, v0, 4, 2
	v_lshl_or_b32 v1, v10, 11, v12
	v_lshl_or_b32 v2, v10, 12, v12
	v_mul_u32_u24_e32 v3, 0x104, v10
	v_add_u32_e32 v3, v3, v12
	v_mul_u32_u24_e32 v4, 0x820, v14
	v_lshl_add_u32 v4, v13, 1, v4
	s_lshl_b32 s22, s88, 5
	v_add_u32_e32 v4, s22, v4
	v_mul_u32_u24_e32 v5, 0x210, v13
	v_lshl_add_u32 v5, v14, 4, v5
	s_lshl_b32 s22, s88, 6
	s_add_i32 s22, s22, 33280
	v_add_u32_e32 v5, s22, v5
	v_mul_u32_u24_e32 v6, 0x210, v10
	v_lshl_add_u32 v6, v11, 7, v6
	v_add_u32_e32 v6, 33280, v6
	v_lshlrev_b32_e32 v7, 7, v11
	v_add_u32_e32 v7, 101376, v7
	v_lshlrev_b32_e32 v8, 2, v13
	v_add_u32_e32 v8, 102400, v8
	v_lshlrev_b32_e32 v9, 8, v13
	v_lshl_add_u32 v9, v14, 4, v9
	s_mov_b32 s4, s86
	s_mov_b32 s6, -1
	s_lshr_b32 s22, s4, 3
	s_and_b32 s23, s4, 7
	s_lshl_b32 s23, s23, 8
	s_lshl_b32 s62, s22, 18
	s_add_u32 s62, s62, s23
	s_add_u32 s14, s46, s62
	s_addc_u32 s15, s47, 0
	s_add_u32 s18, s50, s62
	s_addc_u32 s19, s51, 0
	s_lshl_b32 s62, s22, 19
	s_add_u32 s62, s62, s23
	s_add_u32 s16, s40, s62
	s_addc_u32 s17, s41, 0
	global_load_dwordx4 v[10:13], v1, s[14:15] offset:0
	global_load_dwordx4 v[14:17], v1, s[14:15] offset:16
	global_load_dwordx4 v[18:21], v1, s[14:15] offset:32
	global_load_dwordx4 v[22:25], v1, s[14:15] offset:48
	global_load_dwordx4 v[26:29], v2, s[16:17] offset:0
	global_load_dwordx4 v[30:33], v2, s[16:17] offset:16
	global_load_dwordx4 v[34:37], v2, s[16:17] offset:32
	global_load_dwordx4 v[38:41], v2, s[16:17] offset:48
	global_load_dwordx4 v[42:45], v1, s[18:19] offset:0
	global_load_dwordx4 v[46:49], v1, s[18:19] offset:16
	global_load_dwordx4 v[50:53], v1, s[18:19] offset:32
	global_load_dwordx4 v[54:57], v1, s[18:19] offset:48

; __global__ void __launch_bounds__(NWAVES * 64, 2) fwd_mega(Args args) {
	.amdhsa_kernel _Z8fwd_mega4Args
		.amdhsa_group_segment_fixed_size 0
		.amdhsa_private_segment_fixed_size 0
		.amdhsa_kernarg_size 384
		.amdhsa_user_sgpr_count 2
		.amdhsa_user_sgpr_dispatch_ptr 0
		.amdhsa_user_sgpr_queue_ptr 0
		.amdhsa_user_sgpr_kernarg_segment_ptr 1
		.amdhsa_user_sgpr_dispatch_id 0
		.amdhsa_user_sgpr_kernarg_preload_length 0
		.amdhsa_user_sgpr_kernarg_preload_offset 0
		.amdhsa_user_sgpr_private_segment_size 0
		.amdhsa_uses_dynamic_stack 0
		.amdhsa_enable_private_segment 0
		.amdhsa_system_sgpr_workgroup_id_x 1
		.amdhsa_system_sgpr_workgroup_id_y 0
		.amdhsa_system_sgpr_workgroup_id_z 0
		.amdhsa_system_sgpr_workgroup_info 0
		.amdhsa_system_vgpr_workitem_id 0
		.amdhsa_next_free_vgpr 256
		.amdhsa_next_free_sgpr 102
		.amdhsa_accum_offset 256
		.amdhsa_reserve_vcc 1
		.amdhsa_float_round_mode_32 0
		.amdhsa_float_round_mode_16_64 0
		.amdhsa_float_denorm_mode_32 3
		.amdhsa_float_denorm_mode_16_64 3
		.amdhsa_dx10_clamp 1
		.amdhsa_ieee_mode 1
		.amdhsa_fp16_overflow 0
		.amdhsa_tg_split 0
		.amdhsa_exception_fp_ieee_invalid_op 0
		.amdhsa_exception_fp_denorm_src 0
		.amdhsa_exception_fp_ieee_div_zero 0
		.amdhsa_exception_fp_ieee_overflow 0
		.amdhsa_exception_fp_ieee_underflow 0
		.amdhsa_exception_fp_ieee_inexact 0
		.amdhsa_exception_int_div_zero 0
	.end_amdhsa_kernel

; __global__ void __launch_bounds__(NWAVES * 64, 2) fwd_mega(Args args) {
amdhsa.kernels:
  - .agpr_count:     0
    .args:
      - .offset:         0
        .size:           128
        .value_kind:     by_value
      - .offset:         128
        .size:           4
        .value_kind:     hidden_block_count_x
      - .offset:         132
        .size:           4
        .value_kind:     hidden_block_count_y
      - .offset:         136
        .size:           4
        .value_kind:     hidden_block_count_z
      - .offset:         140
        .size:           2
        .value_kind:     hidden_group_size_x
      - .offset:         142
        .size:           2
        .value_kind:     hidden_group_size_y
      - .offset:         144
        .size:           2
        .value_kind:     hidden_group_size_z
      - .offset:         146
        .size:           2
        .value_kind:     hidden_remainder_x
      - .offset:         148
        .size:           2
        .value_kind:     hidden_remainder_y
      - .offset:         150
        .size:           2
        .value_kind:     hidden_remainder_z
      - .offset:         168
        .size:           8
        .value_kind:     hidden_global_offset_x
      - .offset:         176
        .size:           8
        .value_kind:     hidden_global_offset_y
      - .offset:         184
        .size:           8
        .value_kind:     hidden_global_offset_z
      - .offset:         192
        .size:           2
        .value_kind:     hidden_grid_dims
      - .offset:         216
        .size:           8
        .value_kind:     hidden_multigrid_sync_arg
      - .offset:         248
        .size:           4
        .value_kind:     hidden_dynamic_lds_size
    .group_segment_fixed_size: 0
    .kernarg_segment_align: 8
    .kernarg_segment_size: 384
    .language:       OpenCL C
    .language_version:
      - 2
      - 0
    .max_flat_workgroup_size: 512
    .name:           _Z8fwd_mega4Args
    .private_segment_fixed_size: 0
    .sgpr_count:     108
    .sgpr_spill_count: 0
    .symbol:         _Z8fwd_mega4Args.kd
    .uniform_work_group_size: 1
    .uses_dynamic_stack: false
    .vgpr_count:     256
    .vgpr_spill_count: 0
    .wavefront_size: 64
